# EpiResid first row group: base loads issued with the gate/scale loads (counted vmcnt)
# speedup vs baseline: 1.0053x; 1.0036x over previous
; __device__ __forceinline__ unsigned cvt_pk_bf16(float lo, float hi) { unsigned r; asm volatile("v_cvt_pk_bf16_f32 %0, %1, %2" : "=v"(r) : "v"(lo), "v"(hi)); return r; }
;     __device__ __forceinline__ void operator()(const f32x4 (&acc)[2][2][4][2], const Unit& u, int wr, int wc, int fr, int fq) const {
;         const int row0 = u.pm * BM + wr * 64 + fr, col0 = u.pn * BM + wc * 32 + 4 * fq;
;         const float* gp = gate + (size_t)(u.pm >> 4) * NMOD;
;         f32x4 gv[2][2], sv[2][2];
; #pragma unroll
;         for (int bj = 0; bj < 2; ++bj)
; #pragma unroll
;             for (int n = 0; n < 2; ++n) { gv[bj][n] = *(const f32x4*)(gp + col0 + bj * HALF + n * 16) * (HALFSC ? 0.5f : 1.0f);
;                 if (FOLD) sv[bj][n] = *(const f32x4*)(scn + (size_t)(u.pm >> 4) * NMOD + col0 + bj * HALF + n * 16) + 1.0f; }
; #pragma unroll
;         for (int ai = 0; ai < 2; ++ai)
; #pragma unroll
;             for (int m = 0; m < 4; ++m) { const int row = row0 + ai * HALF + m * 16; const size_t off = (size_t)row * D + col0;
;                 float ssq = 0.f;
; #pragma unroll
;                 for (int bj = 0; bj < 2; ++bj)
; #pragma unroll
;                     for (int n = 0; n < 2; ++n) { const f32x4 bs = *(const f32x4*)(base + off + bj * HALF + n * 16);
;                         const f32x4 o = bs + gv[bj][n] * acc[ai][bj][m][n];
;                         *(f32x4*)(out + off + bj * HALF + n * 16) = o;
;                         if (FOLD) { ssq += (o.x * o.x + o.y * o.y) + (o.z * o.z + o.w * o.w); const f32x4 q = o * sv[bj][n];
;                             u32x2 w; w.x = cvt_pk_bf16(q.x, q.y); w.y = cvt_pk_bf16(q.z, q.w); *(u32x2*)(U2 + off + bj * HALF + n * 16) = w; } }
;                 if (FOLD) { ssq += __shfl_xor(ssq, 16); ssq += __shfl_xor(ssq, 32);
;                     if (fq == 0) part[(size_t)row * 16 + (u.pn & 3) * 4 + wc] = ssq; } }
.LBB0_427:
	s_ashr_i32 s36, s61, 4
	v_lshl_or_b32 v144, s22, 8, v169
	s_mul_i32 s39, s36, 0x9000
	v_lshl_add_u32 v146, s61, 8, v166
	s_mul_hi_i32 s38, s36, 0x9000
	s_add_u32 s36, s46, s39
	v_ashrrev_i32_e32 v145, 31, v144
	v_ashrrev_i32_e32 v147, 31, v146
	s_addc_u32 s37, s47, s38
	v_lshlrev_b64 v[156:157], 2, v[144:145]
	v_lshlrev_b64 v[152:153], 10, v[146:147]
	v_lshl_add_u64 v[158:159], s[36:37], 0, v[156:157]
	s_add_u32 s36, s48, s39
	v_lshl_add_u64 v[160:161], v[152:153], 0, v[144:145]
	v_readlane_b32 s72, v248, 11
	s_addc_u32 s37, s49, s38
	v_lshlrev_b64 v[186:187], 2, v[160:161]
	v_readlane_b32 s73, v248, 12
	global_load_dwordx4 v[148:151], v[158:159], off
	v_lshl_add_u64 v[156:157], s[36:37], 0, v[156:157]
	v_lshl_add_u64 v[208:209], s[72:73], 0, v[186:187]
	global_load_dwordx4 v[152:155], v[208:209], off
	global_load_dwordx4 v[162:165], v[156:157], off
	v_readlane_b32 s74, v248, 13
	v_readlane_b32 s75, v248, 14
	v_readlane_b32 s76, v248, 15
	v_readlane_b32 s77, v248, 16
	v_readlane_b32 s78, v248, 17
	v_readlane_b32 s79, v248, 18
	v_readlane_b32 s72, v248, 0
	v_readlane_b32 s36, v249, 43
	global_load_dwordx4 v[174:177], v[158:159], off offset:64
	global_load_dwordx4 v[178:181], v[158:159], off offset:512
	global_load_dwordx4 v[182:185], v[158:159], off offset:576
	v_readlane_b32 s78, v248, 6
	v_readlane_b32 s79, v248, 7
	v_readlane_b32 s37, v249, 44
	s_lshl_b32 s22, s22, 2
	v_lshl_add_u64 v[212:213], s[78:79], 0, v[186:187]
	global_load_dwordx4 v[186:189], v[156:157], off offset:64
	global_load_dwordx4 v[190:193], v[156:157], off offset:512
	global_load_dwordx4 v[194:197], v[156:157], off offset:576
	global_load_dwordx4 v[236:239], v[208:209], off offset:64
	global_load_dwordx4 v[240:243], v[208:209], off offset:512
	global_load_dwordx4 v[244:247], v[208:209], off offset:576
	v_lshl_add_u64 v[210:211], v[160:161], 1, s[36:37]
	s_and_b32 s38, s22, 12
	v_readlane_b32 s80, v248, 19
	v_readlane_b32 s81, v248, 20
	v_readlane_b32 s82, v248, 21
	v_readlane_b32 s83, v248, 22
	v_readlane_b32 s84, v248, 23
	v_readlane_b32 s85, v248, 24
	v_readlane_b32 s86, v248, 25
	v_readlane_b32 s87, v248, 26
	v_readlane_b32 s73, v248, 1
	v_readlane_b32 s74, v248, 2
	v_readlane_b32 s75, v248, 3
	v_readlane_b32 s76, v248, 4
	v_readlane_b32 s77, v248, 5
	s_waitcnt vmcnt(3)
	v_pk_mul_f32 v[158:159], v[148:149], 0.5 op_sel_hi:[1,0]
	v_pk_mul_f32 v[156:157], v[150:151], 0.5 op_sel_hi:[1,0]
	v_pk_fma_f32 v[198:199], v[124:125], v[158:159], v[152:153]
	v_pk_add_f32 v[162:163], v[162:163], 1.0 op_sel_hi:[1,0]
	v_pk_fma_f32 v[200:201], v[126:127], v[156:157], v[154:155]
	v_pk_add_f32 v[160:161], v[164:165], 1.0 op_sel_hi:[1,0]
	v_pk_mul_f32 v[126:127], v[162:163], v[198:199]
	global_store_dwordx4 v[212:213], v[198:201], off
	v_pk_mul_f32 v[124:125], v[160:161], v[200:201]
	v_cvt_pk_bf16_f32 v126, v126, v127
	v_pk_mul_f32 v[150:151], v[174:175], 0.5 op_sel_hi:[1,0]
	v_cvt_pk_bf16_f32 v127, v124, v125
	global_store_dwordx2 v[210:211], v[126:127], off
	v_pk_mul_f32 v[154:155], v[176:177], 0.5 op_sel_hi:[1,0]
	v_pk_mul_f32 v[152:153], v[180:181], 0.5 op_sel_hi:[1,0]
	v_pk_add_f32 v[126:127], v[186:187], 1.0 op_sel_hi:[1,0]
	v_pk_add_f32 v[124:125], v[188:189], 1.0 op_sel_hi:[1,0]
	v_pk_mul_f32 v[148:149], v[178:179], 0.5 op_sel_hi:[1,0]
	v_mul_f32_e32 v164, v199, v199
	v_fmac_f32_e32 v164, v198, v198
	s_waitcnt vmcnt(4)
	v_pk_fma_f32 v[186:187], v[120:121], v[150:151], v[236:237]
	v_pk_fma_f32 v[188:189], v[122:123], v[154:155], v[238:239]
	v_pk_mul_f32 v[122:123], v[126:127], v[186:187]
	global_store_dwordx4 v[212:213], v[186:189], off offset:64
	v_pk_mul_f32 v[120:121], v[124:125], v[188:189]
	v_cvt_pk_bf16_f32 v122, v122, v123
	v_mul_f32_e32 v180, v189, v189
	v_cvt_pk_bf16_f32 v123, v120, v121
	global_store_dwordx2 v[210:211], v[122:123], off offset:32
	v_pk_add_f32 v[122:123], v[190:191], 1.0 op_sel_hi:[1,0]
	v_pk_add_f32 v[120:121], v[192:193], 1.0 op_sel_hi:[1,0]
	v_fmac_f32_e32 v180, v188, v188
	s_waitcnt vmcnt(5)
	v_pk_fma_f32 v[178:179], v[118:119], v[152:153], v[242:243]
	v_pk_fma_f32 v[176:177], v[116:117], v[148:149], v[240:241]
	global_store_dwordx4 v[212:213], v[176:179], off offset:512
	v_pk_mul_f32 v[118:119], v[122:123], v[176:177]
	v_pk_mul_f32 v[116:117], v[120:121], v[178:179]
	v_cvt_pk_bf16_f32 v118, v118, v119
	v_mul_f32_e32 v175, v201, v201
	v_cvt_pk_bf16_f32 v119, v116, v117
	global_store_dwordx2 v[210:211], v[118:119], off offset:256
	v_fmac_f32_e32 v175, v200, v200
	v_and_b32_e32 v117, 64, v173
	v_add_f32_e32 v164, v164, v175
	v_mul_f32_e32 v175, v187, v187
	v_xor_b32_e32 v116, 16, v173
	v_add_u32_e32 v117, 64, v117
	v_fmac_f32_e32 v175, v186, v186
	v_xor_b32_e32 v118, 32, v173
	v_cmp_lt_i32_e32 vcc, v116, v117
	v_add_f32_e32 v175, v175, v180
	v_add_f32_e32 v164, v164, v175
	v_cndmask_b32_e32 v116, v173, v116, vcc
	v_cmp_lt_i32_e32 vcc, v118, v117
	v_mul_f32_e32 v175, v177, v177
	v_mul_f32_e32 v177, v179, v179
	v_cndmask_b32_e32 v165, v173, v118, vcc
	v_lshlrev_b32_e32 v174, 2, v116
	v_pk_mul_f32 v[118:119], v[184:185], 0.5 op_sel_hi:[1,0]
	v_pk_mul_f32 v[116:117], v[182:183], 0.5 op_sel_hi:[1,0]
	v_fmac_f32_e32 v175, v176, v176
	v_fmac_f32_e32 v177, v178, v178
	v_add_f32_e32 v175, v175, v177
	v_add_f32_e32 v164, v164, v175
	s_waitcnt vmcnt(6)
	v_pk_fma_f32 v[178:179], v[114:115], v[118:119], v[246:247]
	v_pk_fma_f32 v[176:177], v[112:113], v[116:117], v[244:245]
	v_mul_f32_e32 v113, v179, v179
	v_mul_f32_e32 v112, v177, v177
	v_fmac_f32_e32 v112, v176, v176
	v_fmac_f32_e32 v113, v178, v178
	v_add_f32_e32 v112, v112, v113
	v_add_f32_e32 v164, v164, v112
	ds_bpermute_b32 v175, v174, v164
	v_pk_add_f32 v[112:113], v[194:195], 1.0 op_sel_hi:[1,0]
	v_pk_add_f32 v[114:115], v[196:197], 1.0 op_sel_hi:[1,0]
	global_store_dwordx4 v[212:213], v[176:179], off offset:576
	s_waitcnt lgkmcnt(0)
	v_add_f32_e32 v164, v164, v175
	v_lshlrev_b32_e32 v175, 2, v165
	ds_bpermute_b32 v165, v175, v164
	v_pk_mul_f32 v[176:177], v[112:113], v[176:177]
	v_pk_mul_f32 v[178:179], v[114:115], v[178:179]
	v_cvt_pk_bf16_f32 v176, v176, v177
	s_nop 0
	v_cvt_pk_bf16_f32 v177, v178, v179
	global_store_dwordx2 v[210:211], v[176:177], off offset:288
	s_and_saveexec_b64 s[36:37], s[0:1]
	s_cbranch_execz .LBB0_429
	v_readlane_b32 s40, v249, 31
	s_waitcnt lgkmcnt(0)
	v_add_f32_e32 v176, v164, v165
	v_lshlrev_b64 v[164:165], 6, v[146:147]
	v_readlane_b32 s41, v249, 32
	s_lshl_b32 s22, s38, 2
	s_nop 0
	v_lshl_add_u64 v[164:165], s[40:41], 0, v[164:165]
	v_lshl_add_u64 v[164:165], v[164:165], 0, s[22:23]
	s_lshl_b32 s22, s50, 2
	v_lshl_add_u64 v[164:165], v[164:165], 0, s[22:23]
	global_store_dword v[164:165], v176, off

; __device__ __forceinline__ unsigned cvt_pk_bf16(float lo, float hi) { unsigned r; asm volatile("v_cvt_pk_bf16_f32 %0, %1, %2" : "=v"(r) : "v"(lo), "v"(hi)); return r; }
;     __device__ __forceinline__ void operator()(const f32x4 (&acc)[2][2][4][2], const Unit& u, int wr, int wc, int fr, int fq) const {
;         const int row0 = u.pm * BM + wr * 64 + fr, col0 = u.pn * BM + wc * 32 + 4 * fq;
;         const float* gp = gate + (size_t)(u.pm >> 4) * NMOD;
;         f32x4 gv[2][2], sv[2][2];
; #pragma unroll
;         for (int bj = 0; bj < 2; ++bj)
; #pragma unroll
;             for (int n = 0; n < 2; ++n) { gv[bj][n] = *(const f32x4*)(gp + col0 + bj * HALF + n * 16) * (HALFSC ? 0.5f : 1.0f);
;                 if (FOLD) sv[bj][n] = *(const f32x4*)(scn + (size_t)(u.pm >> 4) * NMOD + col0 + bj * HALF + n * 16) + 1.0f; }
; #pragma unroll
;         for (int ai = 0; ai < 2; ++ai)
; #pragma unroll
;             for (int m = 0; m < 4; ++m) { const int row = row0 + ai * HALF + m * 16; const size_t off = (size_t)row * D + col0;
;                 float ssq = 0.f;
; #pragma unroll
;                 for (int bj = 0; bj < 2; ++bj)
; #pragma unroll
;                     for (int n = 0; n < 2; ++n) { const f32x4 bs = *(const f32x4*)(base + off + bj * HALF + n * 16);
;                         const f32x4 o = bs + gv[bj][n] * acc[ai][bj][m][n];
;                         *(f32x4*)(out + off + bj * HALF + n * 16) = o;
;                         if (FOLD) { ssq += (o.x * o.x + o.y * o.y) + (o.z * o.z + o.w * o.w); const f32x4 q = o * sv[bj][n];
;                             u32x2 w; w.x = cvt_pk_bf16(q.x, q.y); w.y = cvt_pk_bf16(q.z, q.w); *(u32x2*)(U2 + off + bj * HALF + n * 16) = w; } }
;                 if (FOLD) { ssq += __shfl_xor(ssq, 16); ssq += __shfl_xor(ssq, 32);
;                     if (fq == 0) part[(size_t)row * 16 + (u.pn & 3) * 4 + wc] = ssq; } }
.LBB0_1102:
	s_ashr_i32 s4, s12, 4
	v_lshl_or_b32 v160, s56, 8, v170
	s_mul_i32 s34, s4, 0x9000
	s_mul_hi_i32 s27, s4, 0x9000
	s_add_u32 s4, s42, s34
	v_ashrrev_i32_e32 v161, 31, v160
	v_lshl_add_u32 v162, s12, 8, v168
	s_addc_u32 s5, s43, s27
	v_lshlrev_b64 v[96:97], 2, v[160:161]
	v_ashrrev_i32_e32 v163, 31, v162
	v_lshl_add_u64 v[98:99], s[4:5], 0, v[96:97]
	s_add_u32 s4, s44, s34
	v_lshlrev_b64 v[104:105], 10, v[162:163]
	v_readlane_b32 s60, v248, 0
	v_lshl_add_u64 v[104:105], v[104:105], 0, v[160:161]
	v_readlane_b32 s66, v248, 6
	v_readlane_b32 s67, v248, 7
	s_addc_u32 s5, s45, s27
	v_lshl_add_u64 v[186:187], s[4:5], 0, v[96:97]
	v_lshl_add_u64 v[194:195], v[104:105], 2, s[66:67]
	global_load_dwordx4 v[100:103], v[98:99], off
	global_load_dwordx4 v[174:177], v[186:187], off
	global_load_dwordx4 v[164:167], v[194:195], off
	v_readlane_b32 s4, v249, 43
	v_readlane_b32 s5, v249, 44
	v_readlane_b32 s61, v248, 1
	v_readlane_b32 s62, v248, 2
	v_lshl_add_u64 v[196:197], v[104:105], 1, s[4:5]
	global_load_dwordx4 v[108:111], v[98:99], off offset:64
	global_load_dwordx4 v[104:107], v[98:99], off offset:512
	s_nop 0
	global_load_dwordx4 v[96:99], v[98:99], off offset:576
	s_nop 0
	global_load_dwordx4 v[178:181], v[186:187], off offset:64
	global_load_dwordx4 v[182:185], v[186:187], off offset:512
	s_nop 0
	global_load_dwordx4 v[186:189], v[186:187], off offset:576
	global_load_dwordx4 v[236:239], v[194:195], off offset:64
	global_load_dwordx4 v[240:243], v[194:195], off offset:512
	global_load_dwordx4 v[244:247], v[194:195], off offset:576
	s_lshl_b32 s4, s56, 2
	s_and_b32 s27, s4, 12
	v_readlane_b32 s63, v248, 3
	v_readlane_b32 s64, v248, 4
	v_readlane_b32 s65, v248, 5
	s_waitcnt vmcnt(3)
	v_pk_fma_f32 v[192:193], v[142:143], v[102:103], v[166:167]
	v_pk_fma_f32 v[190:191], v[140:141], v[100:101], v[164:165]
	v_pk_add_f32 v[166:167], v[174:175], 1.0 op_sel_hi:[1,0]
	v_pk_add_f32 v[164:165], v[176:177], 1.0 op_sel_hi:[1,0]
	v_pk_mul_f32 v[142:143], v[166:167], v[190:191]
	global_store_dwordx4 v[194:195], v[190:193], off
	v_pk_mul_f32 v[140:141], v[164:165], v[192:193]
	v_cvt_pk_bf16_f32 v142, v142, v143
	s_nop 0
	v_cvt_pk_bf16_f32 v143, v140, v141
	global_store_dwordx2 v[196:197], v[142:143], off
	v_pk_add_f32 v[142:143], v[178:179], 1.0 op_sel_hi:[1,0]
	v_pk_add_f32 v[140:141], v[180:181], 1.0 op_sel_hi:[1,0]
	v_mul_f32_e32 v191, v191, v191
	v_mul_f32_e32 v193, v193, v193
	v_fmac_f32_e32 v191, v190, v190
	v_fmac_f32_e32 v193, v192, v192
	s_waitcnt vmcnt(4)
	v_pk_fma_f32 v[174:175], v[136:137], v[108:109], v[236:237]
	v_pk_fma_f32 v[176:177], v[138:139], v[110:111], v[238:239]
	v_pk_mul_f32 v[138:139], v[142:143], v[174:175]
	global_store_dwordx4 v[194:195], v[174:177], off offset:64
	v_pk_mul_f32 v[136:137], v[140:141], v[176:177]
	v_cvt_pk_bf16_f32 v138, v138, v139
	s_nop 0
	v_cvt_pk_bf16_f32 v139, v136, v137
	global_store_dwordx2 v[196:197], v[138:139], off offset:32
	v_pk_add_f32 v[138:139], v[182:183], 1.0 op_sel_hi:[1,0]
	v_pk_add_f32 v[136:137], v[184:185], 1.0 op_sel_hi:[1,0]
	v_mul_f32_e32 v175, v175, v175
	v_mul_f32_e32 v177, v177, v177
	v_fmac_f32_e32 v175, v174, v174
	v_fmac_f32_e32 v177, v176, v176
	v_add_f32_e32 v174, v175, v177
	s_waitcnt vmcnt(5)
	v_pk_fma_f32 v[178:179], v[132:133], v[104:105], v[240:241]
	v_pk_fma_f32 v[180:181], v[134:135], v[106:107], v[242:243]
	v_pk_mul_f32 v[134:135], v[138:139], v[178:179]
	global_store_dwordx4 v[194:195], v[178:181], off offset:512
	v_pk_mul_f32 v[132:133], v[136:137], v[180:181]
	v_cvt_pk_bf16_f32 v134, v134, v135
	v_mul_f32_e32 v175, v179, v179
	v_cvt_pk_bf16_f32 v135, v132, v133
	global_store_dwordx2 v[196:197], v[134:135], off offset:256
	v_mul_f32_e32 v176, v181, v181
	v_pk_add_f32 v[132:133], v[186:187], 1.0 op_sel_hi:[1,0]
	v_add_f32_e32 v186, v191, v193
	v_fmac_f32_e32 v175, v178, v178
	v_fmac_f32_e32 v176, v180, v180
	v_add_f32_e32 v174, v186, v174
	v_add_f32_e32 v175, v175, v176
	v_add_f32_e32 v178, v174, v175
	v_pk_add_f32 v[134:135], v[188:189], 1.0 op_sel_hi:[1,0]
	s_waitcnt vmcnt(6)
	v_pk_fma_f32 v[176:177], v[130:131], v[98:99], v[246:247]
	v_pk_fma_f32 v[174:175], v[128:129], v[96:97], v[244:245]
	v_mul_f32_e32 v129, v177, v177
	v_mul_f32_e32 v128, v175, v175
	v_fmac_f32_e32 v128, v174, v174
	v_fmac_f32_e32 v129, v176, v176
	v_add_f32_e32 v128, v128, v129
	v_add_f32_e32 v128, v178, v128
	ds_bpermute_b32 v129, v207, v128
	global_store_dwordx4 v[194:195], v[174:177], off offset:576
	v_pk_mul_f32 v[130:131], v[134:135], v[176:177]
	s_waitcnt lgkmcnt(0)
	v_add_f32_e32 v128, v128, v129
	ds_bpermute_b32 v129, v208, v128
	v_pk_mul_f32 v[174:175], v[132:133], v[174:175]
	s_nop 0
	v_cvt_pk_bf16_f32 v174, v174, v175
	v_cvt_pk_bf16_f32 v175, v130, v131
	global_store_dwordx2 v[196:197], v[174:175], off offset:288
	s_and_saveexec_b64 s[4:5], s[0:1]
	s_cbranch_execz .LBB0_1104
	v_readlane_b32 s34, v249, 31
	v_lshlrev_b64 v[130:131], 6, v[162:163]
	v_readlane_b32 s35, v249, 32
	s_lshl_b32 s12, s27, 2
	s_waitcnt lgkmcnt(0)
	v_add_f32_e32 v128, v128, v129
	v_lshl_add_u64 v[130:131], s[34:35], 0, v[130:131]
	v_lshl_add_u64 v[130:131], v[130:131], 0, s[12:13]
	s_lshl_b32 s12, s46, 2
	v_lshl_add_u64 v[130:131], v[130:131], 0, s[12:13]
	global_store_dword v[130:131], v128, off

; __device__ __forceinline__ unsigned cvt_pk_bf16(float lo, float hi) { unsigned r; asm volatile("v_cvt_pk_bf16_f32 %0, %1, %2" : "=v"(r) : "v"(lo), "v"(hi)); return r; }
;     __device__ __forceinline__ void operator()(const f32x4 (&acc)[2][2][4][2], const Unit& u, int wr, int wc, int fr, int fq) const {
;         const int row0 = u.pm * BM + wr * 64 + fr, col0 = u.pn * BM + wc * 32 + 4 * fq;
;         const float* gp = gate + (size_t)(u.pm >> 4) * NMOD;
;         f32x4 gv[2][2], sv[2][2];
; #pragma unroll
;         for (int bj = 0; bj < 2; ++bj)
; #pragma unroll
;             for (int n = 0; n < 2; ++n) { gv[bj][n] = *(const f32x4*)(gp + col0 + bj * HALF + n * 16) * (HALFSC ? 0.5f : 1.0f);
;                 if (FOLD) sv[bj][n] = *(const f32x4*)(scn + (size_t)(u.pm >> 4) * NMOD + col0 + bj * HALF + n * 16) + 1.0f; }
; #pragma unroll
;         for (int ai = 0; ai < 2; ++ai)
; #pragma unroll
;             for (int m = 0; m < 4; ++m) { const int row = row0 + ai * HALF + m * 16; const size_t off = (size_t)row * D + col0;
;                 float ssq = 0.f;
; #pragma unroll
;                 for (int bj = 0; bj < 2; ++bj)
; #pragma unroll
;                     for (int n = 0; n < 2; ++n) { const f32x4 bs = *(const f32x4*)(base + off + bj * HALF + n * 16);
;                         const f32x4 o = bs + gv[bj][n] * acc[ai][bj][m][n];
;                         *(f32x4*)(out + off + bj * HALF + n * 16) = o;
;                         if (FOLD) { ssq += (o.x * o.x + o.y * o.y) + (o.z * o.z + o.w * o.w); const f32x4 q = o * sv[bj][n];
;                             u32x2 w; w.x = cvt_pk_bf16(q.x, q.y); w.y = cvt_pk_bf16(q.z, q.w); *(u32x2*)(U2 + off + bj * HALF + n * 16) = w; } }
;                 if (FOLD) { ssq += __shfl_xor(ssq, 16); ssq += __shfl_xor(ssq, 32);
;                     if (fq == 0) part[(size_t)row * 16 + (u.pn & 3) * 4 + wc] = ssq; } }
.LBB0_1272:
	s_ashr_i32 s34, s61, 4
	v_lshl_or_b32 v144, s20, 8, v170
	s_mul_i32 s37, s34, 0x9000
	s_mul_hi_i32 s36, s34, 0x9000
	s_add_u32 s34, s46, s37
	v_ashrrev_i32_e32 v145, 31, v144
	v_lshl_add_u32 v150, s61, 8, v168
	s_addc_u32 s35, s47, s36
	v_lshlrev_b64 v[156:157], 2, v[144:145]
	v_ashrrev_i32_e32 v151, 31, v150
	v_lshl_add_u64 v[160:161], s[34:35], 0, v[156:157]
	s_add_u32 s34, s48, s37
	v_lshlrev_b64 v[152:153], 10, v[150:151]
	v_readlane_b32 s72, v248, 0
	s_addc_u32 s35, s49, s36
	v_lshl_add_u64 v[162:163], v[152:153], 0, v[144:145]
	v_readlane_b32 s78, v248, 6
	v_readlane_b32 s79, v248, 7
	global_load_dwordx4 v[146:149], v[160:161], off
	v_lshl_add_u64 v[164:165], s[34:35], 0, v[156:157]
	v_lshl_add_u64 v[214:215], v[162:163], 2, s[78:79]
	global_load_dwordx4 v[152:155], v[214:215], off
	global_load_dwordx4 v[156:159], v[164:165], off
	v_readlane_b32 s34, v249, 43
	v_readlane_b32 s35, v249, 44
	global_load_dwordx4 v[174:177], v[160:161], off offset:64
	global_load_dwordx4 v[178:181], v[160:161], off offset:512
	global_load_dwordx4 v[182:185], v[160:161], off offset:576
	global_load_dwordx4 v[186:189], v[164:165], off offset:64
	global_load_dwordx4 v[190:193], v[164:165], off offset:512
	global_load_dwordx4 v[194:197], v[164:165], off offset:576
	global_load_dwordx4 v[236:239], v[214:215], off offset:64
	global_load_dwordx4 v[240:243], v[214:215], off offset:512
	global_load_dwordx4 v[244:247], v[214:215], off offset:576
	v_lshl_add_u64 v[216:217], v[162:163], 1, s[34:35]
	s_lshl_b32 s20, s20, 2
	s_and_b32 s36, s20, 12
	v_readlane_b32 s73, v248, 1
	v_readlane_b32 s74, v248, 2
	v_readlane_b32 s75, v248, 3
	v_readlane_b32 s76, v248, 4
	v_readlane_b32 s77, v248, 5
	s_waitcnt vmcnt(3)
	v_pk_mul_f32 v[162:163], v[146:147], 0.5 op_sel_hi:[1,0]
	v_pk_mul_f32 v[160:161], v[148:149], 0.5 op_sel_hi:[1,0]
	v_pk_fma_f32 v[198:199], v[124:125], v[162:163], v[152:153]
	v_pk_add_f32 v[166:167], v[156:157], 1.0 op_sel_hi:[1,0]
	v_pk_fma_f32 v[200:201], v[126:127], v[160:161], v[154:155]
	v_pk_add_f32 v[164:165], v[158:159], 1.0 op_sel_hi:[1,0]
	v_pk_mul_f32 v[126:127], v[166:167], v[198:199]
	global_store_dwordx4 v[214:215], v[198:201], off
	v_pk_mul_f32 v[124:125], v[164:165], v[200:201]
	v_cvt_pk_bf16_f32 v126, v126, v127
	v_pk_mul_f32 v[154:155], v[174:175], 0.5 op_sel_hi:[1,0]
	v_cvt_pk_bf16_f32 v127, v124, v125
	global_store_dwordx2 v[216:217], v[126:127], off
	v_pk_mul_f32 v[158:159], v[176:177], 0.5 op_sel_hi:[1,0]
	v_pk_add_f32 v[148:149], v[186:187], 1.0 op_sel_hi:[1,0]
	v_pk_add_f32 v[126:127], v[188:189], 1.0 op_sel_hi:[1,0]
	v_pk_mul_f32 v[152:153], v[178:179], 0.5 op_sel_hi:[1,0]
	v_pk_mul_f32 v[156:157], v[180:181], 0.5 op_sel_hi:[1,0]
	v_pk_add_f32 v[146:147], v[190:191], 1.0 op_sel_hi:[1,0]
	v_pk_add_f32 v[124:125], v[192:193], 1.0 op_sel_hi:[1,0]
	s_waitcnt vmcnt(4)
	v_pk_fma_f32 v[174:175], v[120:121], v[154:155], v[236:237]
	v_pk_fma_f32 v[176:177], v[122:123], v[158:159], v[238:239]
	v_pk_mul_f32 v[122:123], v[148:149], v[174:175]
	global_store_dwordx4 v[214:215], v[174:177], off offset:64
	v_pk_mul_f32 v[120:121], v[126:127], v[176:177]
	v_cvt_pk_bf16_f32 v122, v122, v123
	s_nop 0
	v_cvt_pk_bf16_f32 v123, v120, v121
	global_store_dwordx2 v[216:217], v[122:123], off offset:32
	v_mul_f32_e32 v175, v175, v175
	v_mul_f32_e32 v177, v177, v177
	v_fmac_f32_e32 v175, v174, v174
	v_fmac_f32_e32 v177, v176, v176
	v_add_f32_e32 v174, v175, v177
	s_waitcnt vmcnt(5)
	v_pk_fma_f32 v[178:179], v[116:117], v[152:153], v[240:241]
	v_pk_fma_f32 v[180:181], v[118:119], v[156:157], v[242:243]
	v_pk_mul_f32 v[118:119], v[146:147], v[178:179]
	global_store_dwordx4 v[214:215], v[178:181], off offset:512
	v_pk_mul_f32 v[116:117], v[124:125], v[180:181]
	v_cvt_pk_bf16_f32 v118, v118, v119
	v_pk_mul_f32 v[120:121], v[182:183], 0.5 op_sel_hi:[1,0]
	v_cvt_pk_bf16_f32 v119, v116, v117
	global_store_dwordx2 v[216:217], v[118:119], off offset:256
	v_mul_f32_e32 v182, v199, v199
	v_mul_f32_e32 v183, v201, v201
	v_fmac_f32_e32 v182, v198, v198
	v_fmac_f32_e32 v183, v200, v200
	v_mul_f32_e32 v175, v179, v179
	v_mul_f32_e32 v176, v181, v181
	v_add_f32_e32 v182, v182, v183
	v_fmac_f32_e32 v175, v178, v178
	v_fmac_f32_e32 v176, v180, v180
	v_pk_mul_f32 v[122:123], v[184:185], 0.5 op_sel_hi:[1,0]
	v_add_f32_e32 v174, v182, v174
	v_add_f32_e32 v175, v175, v176
	v_add_f32_e32 v178, v174, v175
	v_pk_add_f32 v[116:117], v[194:195], 1.0 op_sel_hi:[1,0]
	v_pk_add_f32 v[118:119], v[196:197], 1.0 op_sel_hi:[1,0]
	s_waitcnt vmcnt(6)
	v_pk_fma_f32 v[176:177], v[114:115], v[122:123], v[246:247]
	v_pk_fma_f32 v[174:175], v[112:113], v[120:121], v[244:245]
	v_mul_f32_e32 v113, v177, v177
	v_mul_f32_e32 v112, v175, v175
	v_fmac_f32_e32 v112, v174, v174
	v_fmac_f32_e32 v113, v176, v176
	v_add_f32_e32 v112, v112, v113
	v_add_f32_e32 v112, v178, v112
	ds_bpermute_b32 v113, v207, v112
	global_store_dwordx4 v[214:215], v[174:177], off offset:576
	v_pk_mul_f32 v[114:115], v[118:119], v[176:177]
	s_waitcnt lgkmcnt(0)
	v_add_f32_e32 v112, v112, v113
	ds_bpermute_b32 v113, v208, v112
	v_pk_mul_f32 v[174:175], v[116:117], v[174:175]
	s_nop 0
	v_cvt_pk_bf16_f32 v174, v174, v175
	v_cvt_pk_bf16_f32 v175, v114, v115
	global_store_dwordx2 v[216:217], v[174:175], off offset:288
	s_and_saveexec_b64 s[34:35], s[0:1]
	s_cbranch_execz .LBB0_1274
	v_readlane_b32 s40, v249, 31
	s_waitcnt lgkmcnt(0)
	v_add_f32_e32 v114, v112, v113
	v_lshlrev_b64 v[112:113], 6, v[150:151]
	v_readlane_b32 s41, v249, 32
	s_lshl_b32 s20, s36, 2
	s_nop 0
	v_lshl_add_u64 v[112:113], s[40:41], 0, v[112:113]
	v_lshl_add_u64 v[112:113], v[112:113], 0, s[20:21]
	s_lshl_b32 s20, s50, 2
	v_lshl_add_u64 v[112:113], v[112:113], 0, s[20:21]
	global_store_dword v[112:113], v114, off

; __device__ __forceinline__ unsigned cvt_pk_bf16(float lo, float hi) { unsigned r; asm volatile("v_cvt_pk_bf16_f32 %0, %1, %2" : "=v"(r) : "v"(lo), "v"(hi)); return r; }
;     __device__ __forceinline__ void operator()(const f32x4 (&acc)[2][2][4][2], const Unit& u, int wr, int wc, int fr, int fq) const {
;         const int row0 = u.pm * BM + wr * 64 + fr, col0 = u.pn * BM + wc * 32 + 4 * fq;
;         const float* gp = gate + (size_t)(u.pm >> 4) * NMOD;
;         f32x4 gv[2][2], sv[2][2];
; #pragma unroll
;         for (int bj = 0; bj < 2; ++bj)
; #pragma unroll
;             for (int n = 0; n < 2; ++n) { gv[bj][n] = *(const f32x4*)(gp + col0 + bj * HALF + n * 16) * (HALFSC ? 0.5f : 1.0f);
;                 if (FOLD) sv[bj][n] = *(const f32x4*)(scn + (size_t)(u.pm >> 4) * NMOD + col0 + bj * HALF + n * 16) + 1.0f; }
; #pragma unroll
;         for (int ai = 0; ai < 2; ++ai)
; #pragma unroll
;             for (int m = 0; m < 4; ++m) { const int row = row0 + ai * HALF + m * 16; const size_t off = (size_t)row * D + col0;
;                 float ssq = 0.f;
; #pragma unroll
;                 for (int bj = 0; bj < 2; ++bj)
; #pragma unroll
;                     for (int n = 0; n < 2; ++n) { const f32x4 bs = *(const f32x4*)(base + off + bj * HALF + n * 16);
;                         const f32x4 o = bs + gv[bj][n] * acc[ai][bj][m][n];
;                         *(f32x4*)(out + off + bj * HALF + n * 16) = o;
;                         if (FOLD) { ssq += (o.x * o.x + o.y * o.y) + (o.z * o.z + o.w * o.w); const f32x4 q = o * sv[bj][n];
;                             u32x2 w; w.x = cvt_pk_bf16(q.x, q.y); w.y = cvt_pk_bf16(q.z, q.w); *(u32x2*)(U2 + off + bj * HALF + n * 16) = w; } }
;                 if (FOLD) { ssq += __shfl_xor(ssq, 16); ssq += __shfl_xor(ssq, 32);
;                     if (fq == 0) part[(size_t)row * 16 + (u.pn & 3) * 4 + wc] = ssq; } }
.LBB0_2445:
	s_ashr_i32 s6, s14, 4
	v_lshl_or_b32 v160, s58, 8, v170
	s_mul_i32 s34, s6, 0x9000
	s_mul_hi_i32 s27, s6, 0x9000
	s_add_u32 s6, s45, s34
	v_ashrrev_i32_e32 v161, 31, v160
	v_lshl_add_u32 v162, s14, 8, v168
	s_addc_u32 s7, s46, s27
	v_lshlrev_b64 v[96:97], 2, v[160:161]
	v_ashrrev_i32_e32 v163, 31, v162
	v_lshl_add_u64 v[98:99], s[6:7], 0, v[96:97]
	s_add_u32 s6, s47, s34
	v_lshlrev_b64 v[104:105], 10, v[162:163]
	v_readlane_b32 s60, v248, 0
	v_lshl_add_u64 v[104:105], v[104:105], 0, v[160:161]
	v_readlane_b32 s66, v248, 6
	v_readlane_b32 s67, v248, 7
	s_addc_u32 s7, s48, s27
	v_lshl_add_u64 v[186:187], s[6:7], 0, v[96:97]
	v_lshl_add_u64 v[194:195], v[104:105], 2, s[66:67]
	global_load_dwordx4 v[100:103], v[98:99], off
	global_load_dwordx4 v[174:177], v[186:187], off
	global_load_dwordx4 v[164:167], v[194:195], off
	v_readlane_b32 s6, v249, 43
	v_readlane_b32 s7, v249, 44
	v_readlane_b32 s61, v248, 1
	v_readlane_b32 s62, v248, 2
	v_lshl_add_u64 v[196:197], v[104:105], 1, s[6:7]
	global_load_dwordx4 v[108:111], v[98:99], off offset:64
	global_load_dwordx4 v[104:107], v[98:99], off offset:512
	s_nop 0
	global_load_dwordx4 v[96:99], v[98:99], off offset:576
	s_nop 0
	global_load_dwordx4 v[178:181], v[186:187], off offset:64
	global_load_dwordx4 v[182:185], v[186:187], off offset:512
	s_nop 0
	global_load_dwordx4 v[186:189], v[186:187], off offset:576
	global_load_dwordx4 v[236:239], v[194:195], off offset:64
	global_load_dwordx4 v[240:243], v[194:195], off offset:512
	global_load_dwordx4 v[244:247], v[194:195], off offset:576
	s_lshl_b32 s6, s58, 2
	s_and_b32 s27, s6, 12
	v_readlane_b32 s63, v248, 3
	v_readlane_b32 s64, v248, 4
	v_readlane_b32 s65, v248, 5
	s_waitcnt vmcnt(3)
	v_pk_fma_f32 v[192:193], v[142:143], v[102:103], v[166:167]
	v_pk_fma_f32 v[190:191], v[140:141], v[100:101], v[164:165]
	v_pk_add_f32 v[166:167], v[174:175], 1.0 op_sel_hi:[1,0]
	v_pk_add_f32 v[164:165], v[176:177], 1.0 op_sel_hi:[1,0]
	v_pk_mul_f32 v[142:143], v[166:167], v[190:191]
	global_store_dwordx4 v[194:195], v[190:193], off
	v_pk_mul_f32 v[140:141], v[164:165], v[192:193]
	v_cvt_pk_bf16_f32 v142, v142, v143
	s_nop 0
	v_cvt_pk_bf16_f32 v143, v140, v141
	global_store_dwordx2 v[196:197], v[142:143], off
	v_pk_add_f32 v[142:143], v[178:179], 1.0 op_sel_hi:[1,0]
	v_pk_add_f32 v[140:141], v[180:181], 1.0 op_sel_hi:[1,0]
	v_mul_f32_e32 v191, v191, v191
	v_mul_f32_e32 v193, v193, v193
	v_fmac_f32_e32 v191, v190, v190
	v_fmac_f32_e32 v193, v192, v192
	s_waitcnt vmcnt(4)
	v_pk_fma_f32 v[174:175], v[136:137], v[108:109], v[236:237]
	v_pk_fma_f32 v[176:177], v[138:139], v[110:111], v[238:239]
	v_pk_mul_f32 v[138:139], v[142:143], v[174:175]
	global_store_dwordx4 v[194:195], v[174:177], off offset:64
	v_pk_mul_f32 v[136:137], v[140:141], v[176:177]
	v_cvt_pk_bf16_f32 v138, v138, v139
	s_nop 0
	v_cvt_pk_bf16_f32 v139, v136, v137
	global_store_dwordx2 v[196:197], v[138:139], off offset:32
	v_pk_add_f32 v[138:139], v[182:183], 1.0 op_sel_hi:[1,0]
	v_pk_add_f32 v[136:137], v[184:185], 1.0 op_sel_hi:[1,0]
	v_mul_f32_e32 v175, v175, v175
	v_mul_f32_e32 v177, v177, v177
	v_fmac_f32_e32 v175, v174, v174
	v_fmac_f32_e32 v177, v176, v176
	v_add_f32_e32 v174, v175, v177
	s_waitcnt vmcnt(5)
	v_pk_fma_f32 v[178:179], v[132:133], v[104:105], v[240:241]
	v_pk_fma_f32 v[180:181], v[134:135], v[106:107], v[242:243]
	v_pk_mul_f32 v[134:135], v[138:139], v[178:179]
	global_store_dwordx4 v[194:195], v[178:181], off offset:512
	v_pk_mul_f32 v[132:133], v[136:137], v[180:181]
	v_cvt_pk_bf16_f32 v134, v134, v135
	v_mul_f32_e32 v175, v179, v179
	v_cvt_pk_bf16_f32 v135, v132, v133
	global_store_dwordx2 v[196:197], v[134:135], off offset:256
	v_mul_f32_e32 v176, v181, v181
	v_pk_add_f32 v[132:133], v[186:187], 1.0 op_sel_hi:[1,0]
	v_add_f32_e32 v186, v191, v193
	v_fmac_f32_e32 v175, v178, v178
	v_fmac_f32_e32 v176, v180, v180
	v_add_f32_e32 v174, v186, v174
	v_add_f32_e32 v175, v175, v176
	v_add_f32_e32 v178, v174, v175
	v_pk_add_f32 v[134:135], v[188:189], 1.0 op_sel_hi:[1,0]
	s_waitcnt vmcnt(6)
	v_pk_fma_f32 v[176:177], v[130:131], v[98:99], v[246:247]
	v_pk_fma_f32 v[174:175], v[128:129], v[96:97], v[244:245]
	v_mul_f32_e32 v129, v177, v177
	v_mul_f32_e32 v128, v175, v175
	v_fmac_f32_e32 v128, v174, v174
	v_fmac_f32_e32 v129, v176, v176
	v_add_f32_e32 v128, v128, v129
	v_add_f32_e32 v128, v178, v128
	ds_bpermute_b32 v129, v207, v128
	global_store_dwordx4 v[194:195], v[174:177], off offset:576
	v_pk_mul_f32 v[130:131], v[134:135], v[176:177]
	s_waitcnt lgkmcnt(0)
	v_add_f32_e32 v128, v128, v129
	ds_bpermute_b32 v129, v208, v128
	v_pk_mul_f32 v[174:175], v[132:133], v[174:175]
	s_nop 0
	v_cvt_pk_bf16_f32 v174, v174, v175
	v_cvt_pk_bf16_f32 v175, v130, v131
	global_store_dwordx2 v[196:197], v[174:175], off offset:288
	s_and_saveexec_b64 s[6:7], s[0:1]
	s_cbranch_execz .LBB0_2447
	v_readlane_b32 s34, v249, 31
	v_lshlrev_b64 v[130:131], 6, v[162:163]
	v_readlane_b32 s35, v249, 32
	s_lshl_b32 s14, s27, 2
	s_waitcnt lgkmcnt(0)
	v_add_f32_e32 v128, v128, v129
	v_lshl_add_u64 v[130:131], s[34:35], 0, v[130:131]
	v_lshl_add_u64 v[130:131], v[130:131], 0, s[14:15]
	s_lshl_b32 s14, s49, 2
	v_lshl_add_u64 v[130:131], v[130:131], 0, s[14:15]
	global_store_dword v[130:131], v128, off
